# P5 sample-row small GEMM units: all 24 fragment loads and the 8 row-stat loads issued up front (one memory round trip instead of ~8)
# speedup vs baseline: 1.0071x; 1.0063x over previous
; #define LAS __attribute__((address_space(3)))
; __device__ __forceinline__ int crow(int r, int hi) { return (r & 3) + 8 * (r >> 2) + 4 * hi; }
; #define MFMA32(a, b, c) __builtin_amdgcn_mfma_f32_32x32x16_bf16((a), (b), (c), 0, 0, 0)
; template <int NB, class F> __device__ __forceinline__ void small_gemm(const bf16* A, int K, const bf16* const (&Bs)[NB], int rg, int wave_s, LAS unsigned char* lds, const F& epi) {
;     ...
;     for (int s0 = 0; s0 < steps; s0 += 8) {
;         bf16x8 af[8], bfr[NB][8];
; #pragma unroll
;         for (int s = 0; s < 8; ++s) if (s0 + s < steps) { af[s] = *(const bf16x8*)(ap + 16 * (s0 + s));
; #pragma unroll
;             for (int nb = 0; nb < NB; ++nb) bfr[nb][s] = *(const bf16x8*)(bp[nb] + 16 * (s0 + s)); }
; #pragma unroll
;         for (int s = 0; s < 8; ++s) if (s0 + s < steps) {
; #pragma unroll
;             for (int nb = 0; nb < NB; ++nb) acc[nb] = MFMA32(af[s], bfr[nb][s], acc[nb]); }
;     }
;     LAS float* P = (LAS float*)lds;
; #pragma unroll
;     for (int nb = 0; nb < NB; ++nb)
; #pragma unroll
;         for (int i = 0; i < 16; ++i) P[((w * NB + nb) * 16 + i) * 64 + lane] = acc[nb][i];
;     __syncthreads();
; __global__ void __launch_bounds__(512, 2) hybrid_fwd(Ctx c) {
;     ...
;             for (int ii = 0; ii < 2; ++ii) { const int row = ROW_S0 + 32 * rg + crow(2 * w + ii, hi); const f32x4* sp = (const f32x4*)(SS + (size_t)row * 16);
;                 const f32x4 a = sp[0], b = sp[1], cc = sp[2], dd = sp[3];
.LBB0_1247:
	s_and_b32 s3, s21, 0xffffff00
	s_and_b32 s38, s22, 0x60
	s_or_b32 s38, s3, s38
	s_ashr_i32 s39, s38, 31
	s_and_b32 s2, s22, 0xffffffe0
	s_mov_b32 s42, -1
	s_lshl_b64 s[40:41], s[38:39], 11
	s_add_u32 s40, s16, s40
	v_mbcnt_lo_u32_b32 v0, s42, 0
	v_mbcnt_hi_u32_b32 v0, s42, v0
	s_addc_u32 s41, s17, s41
	s_bitset1_b32 s38, 7
	v_add_u32_e32 v39, s33, v0
	s_ashr_i32 s39, s38, 31
	s_lshl_b64 s[38:39], s[38:39], 11
	s_waitcnt vmcnt(1)
	v_and_b32_e32 v68, 31, v39
	v_mov_b32_e32 v1, v33
	v_lshlrev_b32_e32 v0, 11, v68
	s_add_u32 s38, s16, s38
	v_lshl_add_u64 v[2:3], s[40:41], 0, v[0:1]
	s_addc_u32 s39, s17, s39
	s_and_b32 s40, s24, 0xe0
	v_bfe_u32 v69, v39, 5, 1
	v_or_b32_e32 v6, s40, v68
	v_lshl_add_u64 v[0:1], s[38:39], 0, v[0:1]
	v_mov_b32_e32 v5, v33
	v_lshlrev_b32_e32 v4, 4, v69
	v_lshl_or_b32 v32, v6, 11, v36
	v_lshl_add_u64 v[6:7], v[0:1], 0, s[4:5]
	v_lshl_add_u64 v[2:3], v[2:3], 0, s[4:5]
	v_lshl_add_u64 v[64:65], v[6:7], 0, v[4:5]
	v_lshl_add_u64 v[6:7], s[10:11], 0, v[32:33]
	v_lshl_add_u64 v[34:35], v[2:3], 0, v[4:5]
	v_lshl_add_u64 v[66:67], v[6:7], 0, v[4:5]
	s_add_i32 s38, s20, s40
	v_lshl_or_b32 v180, v69, 2, s38
	v_mov_b32_e32 v181, v33
	v_lshlrev_b64 v[180:181], 6, v[180:181]
	v_lshl_add_u64 v[180:181], s[12:13], 0, v[180:181]
	global_load_dwordx4 v[70:73], v[66:67], off
	global_load_dwordx4 v[102:105], v[34:35], off
	global_load_dwordx4 v[192:195], v[64:65], off
	global_load_dwordx4 v[74:77], v[66:67], off offset:32
	global_load_dwordx4 v[106:109], v[34:35], off offset:32
	global_load_dwordx4 v[196:199], v[64:65], off offset:32
	global_load_dwordx4 v[78:81], v[66:67], off offset:64
	global_load_dwordx4 v[110:113], v[34:35], off offset:64
	global_load_dwordx4 v[200:203], v[64:65], off offset:64
	global_load_dwordx4 v[82:85], v[66:67], off offset:96
	global_load_dwordx4 v[114:117], v[34:35], off offset:96
	global_load_dwordx4 v[204:207], v[64:65], off offset:96
	global_load_dwordx4 v[86:89], v[66:67], off offset:128
	global_load_dwordx4 v[118:121], v[34:35], off offset:128
	global_load_dwordx4 v[208:211], v[64:65], off offset:128
	global_load_dwordx4 v[90:93], v[66:67], off offset:160
	global_load_dwordx4 v[122:125], v[34:35], off offset:160
	global_load_dwordx4 v[224:227], v[64:65], off offset:160
	global_load_dwordx4 v[94:97], v[66:67], off offset:192
	global_load_dwordx4 v[184:187], v[34:35], off offset:192
	global_load_dwordx4 v[216:219], v[64:65], off offset:192
	global_load_dwordx4 v[98:101], v[66:67], off offset:224
	global_load_dwordx4 v[188:191], v[34:35], off offset:224
	global_load_dwordx4 v[220:223], v[64:65], off offset:224
	global_load_dwordx4 v[148:151], v[180:181], off
	global_load_dwordx4 v[152:155], v[180:181], off offset:16
	global_load_dwordx4 v[156:159], v[180:181], off offset:32
	global_load_dwordx4 v[160:163], v[180:181], off offset:48
	global_load_dwordx4 v[164:167], v[180:181], off offset:64
	global_load_dwordx4 v[168:171], v[180:181], off offset:80
	global_load_dwordx4 v[172:175], v[180:181], off offset:96
	global_load_dwordx4 v[176:179], v[180:181], off offset:112
	s_add_i32 s38, s20, s40
	v_and_b32_e32 v32, 63, v39
	v_lshl_add_u32 v32, v32, 2, 0
	v_add_u32_e32 v39, s18, v32
	s_ashr_i32 s3, s2, 31
	s_lshl_b64 s[2:3], s[2:3], 1
	s_add_u32 s2, s30, s2
	s_addc_u32 s3, s31, s3
	s_add_i32 s37, s37, s15
	s_add_i32 s21, s21, s80
	s_add_i32 s22, s22, s23
	s_add_i32 s24, s24, s25
	s_cmpk_gt_i32 s37, 0x2bf
	v_mov_b32_e32 v57, v33
	v_lshl_or_b32 v56, v69, 2, s38
	v_add_u32_e32 v58, s19, v32
	v_lshlrev_b32_e32 v32, 1, v68
	v_lshl_add_u64 v[34:35], s[2:3], 0, v[32:33]
	v_or_b32_e32 v32, 1, v56
	v_lshlrev_b64 v[52:53], 6, v[32:33]
	v_lshlrev_b64 v[44:45], 6, v[56:57]
	v_lshl_add_u64 v[44:45], s[12:13], 0, v[44:45]
	v_mad_u64_u32 v[46:47], s[2:3], v56, s36, v[34:35]
	s_waitcnt vmcnt(30)
	v_mfma_f32_32x32x16_bf16 v[16:31], v[70:73], v[102:105], 0
	s_waitcnt vmcnt(29)
	v_mfma_f32_32x32x16_bf16 v[0:15], v[70:73], v[192:195], 0
	s_waitcnt vmcnt(27)
	v_mfma_f32_32x32x16_bf16 v[16:31], v[74:77], v[106:109], v[16:31]
	s_waitcnt vmcnt(26)
	v_mfma_f32_32x32x16_bf16 v[0:15], v[74:77], v[196:199], v[0:15]
	s_waitcnt vmcnt(24)
	v_mfma_f32_32x32x16_bf16 v[16:31], v[78:81], v[110:113], v[16:31]
	s_waitcnt vmcnt(23)
	v_mfma_f32_32x32x16_bf16 v[0:15], v[78:81], v[200:203], v[0:15]
	s_waitcnt vmcnt(21)
	v_mfma_f32_32x32x16_bf16 v[16:31], v[82:85], v[114:117], v[16:31]
	s_waitcnt vmcnt(20)
	v_mfma_f32_32x32x16_bf16 v[0:15], v[82:85], v[204:207], v[0:15]
	s_waitcnt vmcnt(18)
	v_mfma_f32_32x32x16_bf16 v[16:31], v[86:89], v[118:121], v[16:31]
	s_waitcnt vmcnt(17)
	v_mfma_f32_32x32x16_bf16 v[0:15], v[86:89], v[208:211], v[0:15]
	s_waitcnt vmcnt(15)
	v_mfma_f32_32x32x16_bf16 v[16:31], v[90:93], v[122:125], v[16:31]
	s_waitcnt vmcnt(14)
	v_mfma_f32_32x32x16_bf16 v[0:15], v[90:93], v[224:227], v[0:15]
	s_waitcnt vmcnt(12)
	v_mfma_f32_32x32x16_bf16 v[16:31], v[94:97], v[184:187], v[16:31]
	s_waitcnt vmcnt(11)
	v_mfma_f32_32x32x16_bf16 v[0:15], v[94:97], v[216:219], v[0:15]
	s_waitcnt vmcnt(9)
	v_mfma_f32_32x32x16_bf16 v[16:31], v[98:101], v[188:191], v[16:31]
	s_waitcnt vmcnt(8)
	v_mfma_f32_32x32x16_bf16 v[0:15], v[98:101], v[220:223], v[0:15]
	s_nop 6
	ds_write2st64_b32 v39, v16, v17 offset1:1
	ds_write2st64_b32 v39, v18, v19 offset0:2 offset1:3
	ds_write2st64_b32 v39, v20, v21 offset0:4 offset1:5
	ds_write2st64_b32 v39, v22, v23 offset0:6 offset1:7
	ds_write2st64_b32 v39, v24, v25 offset0:8 offset1:9
	ds_write2st64_b32 v39, v26, v27 offset0:10 offset1:11
	ds_write2st64_b32 v39, v28, v29 offset0:12 offset1:13
	ds_write2st64_b32 v39, v30, v31 offset0:14 offset1:15
	ds_write2st64_b32 v39, v0, v1 offset0:16 offset1:17
	ds_write2st64_b32 v39, v2, v3 offset0:18 offset1:19
	ds_write2st64_b32 v39, v4, v5 offset0:20 offset1:21
	ds_write2st64_b32 v39, v6, v7 offset0:22 offset1:23
	ds_write2st64_b32 v39, v8, v9 offset0:24 offset1:25
	ds_write2st64_b32 v39, v10, v11 offset0:26 offset1:27
	ds_write2st64_b32 v39, v12, v13 offset0:28 offset1:29
	ds_write2st64_b32 v39, v14, v15 offset0:30 offset1:31
	s_waitcnt lgkmcnt(0)
	s_barrier
; __device__ __forceinline__ unsigned f2bf(float f) { unsigned u = __builtin_bit_cast(unsigned, f); return (u + 0x7fffu + ((u >> 16) & 1u)) >> 16; }
; __device__ __forceinline__ float silu_f(float x) { return x * sigm_f(x); }
; __device__ __forceinline__ int crow(int r, int hi) { return (r & 3) + 8 * (r >> 2) + 4 * hi; }
; template <int NB, class F> __device__ __forceinline__ void small_gemm(const bf16* A, int K, const bf16* const (&Bs)[NB], int rg, int wave_s, LAS unsigned char* lds, const F& epi) {
;     ...
;     float v[NB][2];
; #pragma unroll
;     for (int nb = 0; nb < NB; ++nb)
; #pragma unroll
;         for (int ii = 0; ii < 2; ++ii) { float t = 0.f;
; #pragma unroll
;             for (int ww = 0; ww < 8; ++ww) t += P[((ww * NB + nb) * 16 + 2 * w + ii) * 64 + lane];
;             v[nb][ii] = t; }
;     epi(v, w, r32, hi);
; __global__ void __launch_bounds__(512, 2) hybrid_fwd(Ctx c) {
;     ...
;             for (int ii = 0; ii < 2; ++ii) { const int row = ROW_S0 + 32 * rg + crow(2 * w + ii, hi); const f32x4* sp = (const f32x4*)(SS + (size_t)row * 16);
;                 const f32x4 a = sp[0], b = sp[1], cc = sp[2], dd = sp[3];
;                 const float tot = ((a[0] + a[1]) + (a[2] + a[3])) + ((b[0] + b[1]) + (b[2] + b[3])) + ((cc[0] + cc[1]) + (cc[2] + cc[3])) + ((dd[0] + dd[1]) + (dd[2] + dd[3]));
;                 const float rstd = 1.f / sqrtf(tot * (1.f / D) + 1e-6f);
;                 HID[(size_t)row * DFF + 32 * cg + r32] = (bf16)f2bf(silu_f(v[0][ii] * rstd) * (v[1][ii] * rstd)); } });
	v_lshl_add_u64 v[16:17], s[12:13], 0, v[52:53]
	ds_read2st64_b32 v[18:19], v58 offset1:1
	ds_read2st64_b32 v[20:21], v58 offset0:32 offset1:33
	ds_read2st64_b32 v[22:23], v58 offset0:48 offset1:49
	ds_read2st64_b32 v[24:25], v58 offset0:16 offset1:17
	ds_read2st64_b32 v[26:27], v58 offset0:64 offset1:65
	ds_read2st64_b32 v[28:29], v58 offset0:96 offset1:97
	ds_read2st64_b32 v[30:31], v58 offset0:112 offset1:113
	ds_read2st64_b32 v[40:41], v58 offset0:80 offset1:81
	ds_read2st64_b32 v[42:43], v58 offset0:128 offset1:129
	ds_read2st64_b32 v[44:45], v58 offset0:160 offset1:161
	ds_read2st64_b32 v[48:49], v58 offset0:176 offset1:177
	ds_read2st64_b32 v[50:51], v58 offset0:144 offset1:145
	ds_read2st64_b32 v[52:53], v58 offset0:192 offset1:193
	ds_read2st64_b32 v[54:55], v58 offset0:224 offset1:225
	ds_read2st64_b32 v[56:57], v58 offset0:240 offset1:241
	ds_read2st64_b32 v[58:59], v58 offset0:208 offset1:209
	s_waitcnt lgkmcnt(14)
	v_add_f32_e32 v18, 0, v18
	v_add_f32_e32 v18, v18, v20
	s_waitcnt lgkmcnt(11)
	v_add_f32_e32 v18, v18, v26
	s_waitcnt lgkmcnt(10)
	v_add_f32_e32 v18, v18, v28
	s_waitcnt lgkmcnt(7)
	v_add_f32_e32 v18, v18, v42
	s_waitcnt lgkmcnt(6)
	v_add_f32_e32 v18, v18, v44
	s_waitcnt lgkmcnt(3)
	v_add_f32_e32 v18, v18, v52
	s_waitcnt lgkmcnt(2)
	v_add_f32_e32 v18, v18, v54
	v_add_f32_e32 v24, 0, v24
	v_add_f32_e32 v20, v24, v22
	v_add_f32_e32 v20, v20, v40
	v_add_f32_e32 v20, v20, v30
	v_add_f32_e32 v20, v20, v50
	v_add_f32_e32 v20, v20, v48
	s_waitcnt lgkmcnt(0)
	v_add_f32_e32 v20, v20, v58
	v_add_f32_e32 v20, v20, v56
	s_waitcnt vmcnt(4)
	v_add_f32_e32 v0, v148, v149
	v_add_f32_e32 v1, v150, v151
	v_add_f32_e32 v2, v152, v153
	v_add_f32_e32 v3, v154, v155
	v_add_f32_e32 v4, v156, v157
	v_add_f32_e32 v5, v158, v159
	v_add_f32_e32 v0, v0, v1
	v_add_f32_e32 v1, v2, v3
	v_add_f32_e32 v6, v160, v161
	v_add_f32_e32 v7, v162, v163
	v_add_f32_e32 v2, v4, v5
	v_add_f32_e32 v0, v0, v1
	v_add_f32_e32 v3, v6, v7
	v_add_f32_e32 v0, v0, v2
	v_add_f32_e32 v0, v0, v3
	v_fmamk_f32 v0, v0, 0x3a800000, v37
	v_mul_f32_e32 v1, 0x4f800000, v0
	v_cmp_gt_f32_e32 vcc, s26, v0
	s_nop 1
	v_cndmask_b32_e32 v0, v0, v1, vcc
	v_sqrt_f32_e32 v1, v0
	s_nop 0
	v_add_u32_e32 v2, -1, v1
	v_add_u32_e32 v3, 1, v1
	v_fma_f32 v4, -v2, v1, v0
	v_fma_f32 v5, -v3, v1, v0
	v_cmp_ge_f32_e64 s[2:3], 0, v4
	s_nop 1
	v_cndmask_b32_e64 v1, v1, v2, s[2:3]
	v_cmp_lt_f32_e64 s[2:3], 0, v5
	s_nop 1
	v_cndmask_b32_e64 v1, v1, v3, s[2:3]
	v_mul_f32_e32 v2, 0x37800000, v1
	v_cndmask_b32_e32 v1, v1, v2, vcc
	v_cmp_class_f32_e32 vcc, v0, v38
	s_nop 1
	v_cndmask_b32_e32 v0, v1, v0, vcc
	v_div_scale_f32 v1, s[2:3], v0, v0, 1.0
	v_rcp_f32_e32 v3, v1
	v_div_scale_f32 v2, vcc, 1.0, v0, 1.0
	v_fma_f32 v4, -v1, v3, 1.0
	v_fmac_f32_e32 v3, v4, v3
	v_mul_f32_e32 v4, v2, v3
	v_fma_f32 v5, -v1, v4, v2
	v_fmac_f32_e32 v4, v5, v3
	v_fma_f32 v1, -v1, v4, v2
	v_div_fmas_f32 v1, v1, v3, v4
	v_div_fixup_f32 v0, v1, v0, 1.0
	v_mul_f32_e32 v1, v18, v0
	v_mul_f32_e32 v2, 0xbfb8aa3b, v1
	v_exp_f32_e32 v2, v2
	v_mul_f32_e32 v0, v20, v0
	v_add_f32_e32 v18, 0, v19
	v_add_f32_e32 v18, v18, v21
	v_add_f32_e32 v2, 1.0, v2
	v_rcp_f32_e32 v2, v2
	v_add_f32_e32 v18, v18, v27
	v_add_f32_e32 v18, v18, v29
	v_add_f32_e32 v18, v18, v43
	v_mul_f32_e32 v1, v1, v2
	v_mul_f32_e32 v0, v0, v1
	v_bfe_u32 v1, v0, 16, 1
	v_add3_u32 v0, v0, v1, s27
	global_store_short_d16_hi v[46:47], v0, off
	v_mad_u64_u32 v[16:17], s[2:3], v32, s36, v[34:35]
	v_add_f32_e32 v18, v18, v45
	v_add_f32_e32 v18, v18, v53
	v_add_f32_e32 v18, v18, v55
	v_add_f32_e32 v19, 0, v25
	v_add_f32_e32 v19, v19, v23
	v_add_f32_e32 v19, v19, v41
	v_add_f32_e32 v19, v19, v31
	v_add_f32_e32 v19, v19, v51
	v_add_f32_e32 v19, v19, v49
	v_add_f32_e32 v19, v19, v59
	v_add_f32_e32 v19, v19, v57
	s_waitcnt vmcnt(1)
	v_add_f32_e32 v0, v164, v165
	v_add_f32_e32 v1, v166, v167
	v_add_f32_e32 v2, v168, v169
	v_add_f32_e32 v3, v170, v171
	v_add_f32_e32 v4, v172, v173
	v_add_f32_e32 v5, v174, v175
	v_add_f32_e32 v0, v0, v1
	v_add_f32_e32 v1, v2, v3
	v_add_f32_e32 v6, v176, v177
	v_add_f32_e32 v7, v178, v179
	v_add_f32_e32 v2, v4, v5
	v_add_f32_e32 v0, v0, v1
	v_add_f32_e32 v3, v6, v7
	v_add_f32_e32 v0, v0, v2
	v_add_f32_e32 v0, v0, v3
	v_fmamk_f32 v0, v0, 0x3a800000, v37
	v_mul_f32_e32 v1, 0x4f800000, v0
	v_cmp_gt_f32_e32 vcc, s26, v0
	s_nop 1
	v_cndmask_b32_e32 v0, v0, v1, vcc
	v_sqrt_f32_e32 v1, v0
	s_nop 0
	v_add_u32_e32 v2, -1, v1
	v_add_u32_e32 v3, 1, v1
	v_fma_f32 v4, -v2, v1, v0
	v_fma_f32 v5, -v3, v1, v0
	v_cmp_ge_f32_e64 s[2:3], 0, v4
	s_nop 1
	v_cndmask_b32_e64 v1, v1, v2, s[2:3]
	v_cmp_lt_f32_e64 s[2:3], 0, v5
	s_nop 1
	v_cndmask_b32_e64 v1, v1, v3, s[2:3]
	v_mul_f32_e32 v2, 0x37800000, v1
	v_cndmask_b32_e32 v1, v1, v2, vcc
	v_cmp_class_f32_e32 vcc, v0, v38
	s_nop 1
	v_cndmask_b32_e32 v0, v1, v0, vcc
	v_div_scale_f32 v1, s[2:3], v0, v0, 1.0
	v_rcp_f32_e32 v3, v1
	v_div_scale_f32 v2, vcc, 1.0, v0, 1.0
	v_fma_f32 v4, -v1, v3, 1.0
	v_fmac_f32_e32 v3, v4, v3
	v_mul_f32_e32 v4, v2, v3
	v_fma_f32 v5, -v1, v4, v2
	v_fmac_f32_e32 v4, v5, v3
	v_fma_f32 v1, -v1, v4, v2
	v_div_fmas_f32 v1, v1, v3, v4
	v_div_fixup_f32 v0, v1, v0, 1.0
	v_mul_f32_e32 v1, v18, v0
	v_mul_f32_e32 v2, 0xbfb8aa3b, v1
	v_exp_f32_e32 v2, v2
	v_mul_f32_e32 v0, v19, v0
	v_add_f32_e32 v2, 1.0, v2
	v_rcp_f32_e32 v2, v2
	s_nop 0
	v_mul_f32_e32 v1, v1, v2
	v_mul_f32_e32 v0, v0, v1
	v_bfe_u32 v1, v0, 16, 1
	v_add3_u32 v0, v0, v1, s27
	global_store_short_d16_hi v[16:17], v0, off
	s_barrier
	s_cbranch_scc0 .LBB0_1247
